# code placement: K-loop head moved 4 bytes to an 8-byte phase (same phase as the baseline's loop head)
# baseline (speedup 1.0000x reference)
; #define PG8_LDA(dst, b, h) do { _Pragma("unroll") for (int m = 0; m < 4; ++m) _Pragma("unroll") for (int k = 0; k < 2; ++k) dst[m][k] = *(const LAS bf16x8*)(lds + PG8_SA(b, h) + aoff + m * 2048 + k * 1024); } while (0)
; #define PG8_LDB(dst, b, h) do { _Pragma("unroll") for (int n = 0; n < 2; ++n) _Pragma("unroll") for (int k = 0; k < 2; ++k) dst[n][k] = *(const LAS bf16x8*)(lds + PG8_SB(b, h) + boff + n * 2048 + k * 1024); } while (0)
; #define PG8_SCHED __builtin_amdgcn_sched_barrier(0)
; #define PG8_STA(bufoff, gbase, ld) PG8_STAGE(bufoff, gbase, RA0 * (unsigned)(ld) + CC0, RA1 * (unsigned)(ld) + CC1)
; __device__ __forceinline__ void gemm_phase(LAS unsigned char* lds, const Sched& S, const Epi& E) {
;     ...
;         const char* nA = has_next ? nxt.a : cA; const char* nB = has_next ? nxt.b : cB;
;         const int nlda = has_next ? nxt.lda : lda, nldb = has_next ? nxt.ldb : ldb;
;         const size_t hA = (size_t)HALF * lda * 2;
;         const int nt = cur.nt;
;         const int nt_main = has_next ? nt : nt - 2;
;         for (int t = 0; t < nt_main; t += 2) {
;             const bool last = (t == nt - 2);
;             const char* a1 = cA + (size_t)(t + 1) * kstep;
;             const char* a2 = last ? nA : cA + (size_t)(t + 2) * kstep; const char* b2 = last ? nB : cB + (size_t)(t + 2) * kstep;
;             const char* a3 = a2 + kstep; const char* b3 = b2 + kstep;
;             const int xlda = last ? nlda : lda, xldb = last ? nldb : ldb;
;             const size_t xhA = (size_t)HALF * xlda * 2, xhB = (size_t)HALF * xldb * 2;
;             PG8_LDB(B0, 0, 0); PG8_LDB(B1, 0, 1); PG8_SCHED; PG8_LDA(At, 0, 0); PG8_STA(PG8_SA(1, 1), a1 + hA, lda);
;     ...
; #pragma unroll
;         for (int a = 0; a < 2; ++a)
; #pragma unroll
;             for (int b = 0; b < 2; ++b)
; #pragma unroll
;                 for (int m = 0; m < 4; ++m)
; #pragma unroll
;                     for (int n = 0; n < 2; ++n) acc[a][b][m][n] = (f32x4){0.f, 0.f, 0.f, 0.f};
.LBB0_261:
	s_mov_b32 s21, s31
	s_lshl_b64 s[66:67], s[20:21], 8
	s_add_i32 s21, s60, -2
	s_and_b64 s[26:27], s[42:43], exec
	s_cselect_b32 s68, s60, s21
	s_cmp_lt_i32 s68, 1
	s_cbranch_scc1 .LBB0_274
	s_add_u32 vcc_lo, s96, 0x80
	s_addc_u32 vcc_hi, s97, 0
	s_add_u32 s2, s8, 0x100
	s_addc_u32 s72, s9, 0
	v_mad_u64_u32 v[2:3], s[8:9], s20, v235, v[206:207]
	v_mov_b32_e32 v3, v1
	s_waitcnt lgkmcnt(0)
	v_lshl_add_u64 v[130:131], s[66:67], 0, v[2:3]
	v_mad_u64_u32 v[2:3], s[8:9], s20, v236, v[208:209]
	v_mov_b32_e32 v3, v1
	v_lshl_add_u64 v[132:133], s[66:67], 0, v[2:3]
	s_mov_b32 s3, s92
	s_mov_b32 s8, 0
	v_mov_b64_e32 v[2:3], 0
	v_mov_b64_e32 v[4:5], 0
	v_mov_b64_e32 v[6:7], 0
	v_mov_b64_e32 v[8:9], 0
	v_mov_b64_e32 v[10:11], 0
	v_mov_b64_e32 v[12:13], 0
	v_mov_b64_e32 v[14:15], 0
	v_mov_b64_e32 v[16:17], 0
	v_mov_b64_e32 v[18:19], 0
	v_mov_b64_e32 v[20:21], 0
	v_mov_b64_e32 v[22:23], 0
	v_mov_b64_e32 v[24:25], 0
	v_mov_b64_e32 v[26:27], 0
	v_mov_b64_e32 v[28:29], 0
	v_mov_b64_e32 v[30:31], 0
	v_mov_b64_e32 v[32:33], 0
	v_mov_b64_e32 v[34:35], 0
	v_mov_b64_e32 v[36:37], 0
	v_mov_b64_e32 v[38:39], 0
	v_mov_b64_e32 v[40:41], 0
	v_mov_b64_e32 v[42:43], 0
	v_mov_b64_e32 v[44:45], 0
	v_mov_b64_e32 v[46:47], 0
	v_mov_b64_e32 v[48:49], 0
	v_mov_b64_e32 v[50:51], 0
	v_mov_b64_e32 v[52:53], 0
	v_mov_b64_e32 v[54:55], 0
	v_mov_b64_e32 v[56:57], 0
	v_mov_b64_e32 v[58:59], 0
	v_mov_b64_e32 v[60:61], 0
	v_mov_b64_e32 v[62:63], 0
	v_mov_b64_e32 v[64:65], 0
	v_mov_b64_e32 v[66:67], 0
	v_mov_b64_e32 v[68:69], 0
	v_mov_b64_e32 v[70:71], 0
	v_mov_b64_e32 v[72:73], 0
	v_mov_b64_e32 v[74:75], 0
	v_mov_b64_e32 v[76:77], 0
	v_mov_b64_e32 v[78:79], 0
	v_mov_b64_e32 v[80:81], 0
	v_mov_b64_e32 v[82:83], 0
	v_mov_b64_e32 v[84:85], 0
	v_mov_b64_e32 v[86:87], 0
	v_mov_b64_e32 v[88:89], 0
	v_mov_b64_e32 v[90:91], 0
	v_mov_b64_e32 v[92:93], 0
	v_mov_b64_e32 v[94:95], 0
	v_mov_b64_e32 v[96:97], 0
	v_mov_b64_e32 v[98:99], 0
	v_mov_b64_e32 v[100:101], 0
	v_mov_b64_e32 v[102:103], 0
	v_mov_b64_e32 v[104:105], 0
	v_mov_b64_e32 v[106:107], 0
	v_mov_b64_e32 v[108:109], 0
	v_mov_b64_e32 v[110:111], 0
	v_mov_b64_e32 v[112:113], 0
	v_mov_b64_e32 v[114:115], 0
	v_mov_b64_e32 v[116:117], 0
	v_mov_b64_e32 v[118:119], 0
	v_mov_b64_e32 v[120:121], 0
	v_mov_b64_e32 v[122:123], 0
	v_mov_b64_e32 v[124:125], 0
	v_mov_b64_e32 v[126:127], 0
	v_mov_b64_e32 v[128:129], 0
	s_nop 0
